# GEMM epilogue stores of the five all-workgroup GEMM phases marked non-temporal (less dirty L2 data to write back at the grid barriers)
# speedup vs baseline: 1.0142x; 1.0142x over previous
.LBB0_126:
	s_lshl_b32 s15, s46, 8
	s_add_i32 s22, s15, 0xfffff300
	s_cmp_lt_i32 s46, 13
	s_mov_b32 s23, 0xf000000
	s_movk_i32 s13, 0xd00
	s_cselect_b32 s23, s23, 0x1c000000
	s_cselect_b32 s15, s15, s22
	s_cselect_b32 s13, s13, 0x1000
	s_add_u32 s22, s78, s23
	v_or_b32_e32 v146, s15, v149
	s_addc_u32 s23, s79, 0
	v_lshl_add_u32 v155, s20, 8, v1
	v_ashrrev_i32_e32 v147, 31, v146
	v_lshl_add_u64 v[146:147], v[146:147], 1, s[22:23]
	v_mad_i64_i32 v[156:157], s[22:23], s13, v155, 0
	v_lshl_add_u64 v[156:157], v[156:157], 1, v[146:147]
	v_cvt_pk_bf16_f32 v126, v126, v127
	v_cvt_pk_bf16_f32 v127, v128, v129
	v_cvt_pk_bf16_f32 v128, v122, v123
	v_cvt_pk_bf16_f32 v129, v124, v125
	global_store_dwordx4 v[156:157], v[126:129], off nt
	v_cvt_pk_bf16_f32 v114, v114, v115
	v_cvt_pk_bf16_f32 v115, v116, v117
	v_cvt_pk_bf16_f32 v116, v106, v107
	v_or_b32_e32 v106, 16, v155
	v_mad_i64_i32 v[106:107], s[22:23], s13, v106, 0
	v_cvt_pk_bf16_f32 v117, v108, v109
	global_store_dwordx4 v[156:157], v[114:117], off offset:256 nt
	s_andn2_b64 vcc, exec, s[0:1]
	s_mov_b64 s[0:1], -1
	v_lshl_add_u64 v[114:115], v[106:107], 1, v[146:147]
	v_cvt_pk_bf16_f32 v106, v118, v119
	v_cvt_pk_bf16_f32 v107, v120, v121
	v_cvt_pk_bf16_f32 v108, v110, v111
	v_cvt_pk_bf16_f32 v109, v112, v113
	global_store_dwordx4 v[114:115], v[106:109], off nt
	v_cvt_pk_bf16_f32 v98, v98, v99
	v_cvt_pk_bf16_f32 v99, v100, v101
	v_cvt_pk_bf16_f32 v100, v90, v91
	v_or_b32_e32 v90, 32, v155
	v_mad_i64_i32 v[90:91], s[22:23], s13, v90, 0
	v_cvt_pk_bf16_f32 v101, v92, v93
	global_store_dwordx4 v[114:115], v[98:101], off offset:256 nt
	s_nop 1
	v_lshl_add_u64 v[98:99], v[90:91], 1, v[146:147]
	v_cvt_pk_bf16_f32 v90, v102, v103
	v_cvt_pk_bf16_f32 v91, v104, v105
	v_cvt_pk_bf16_f32 v92, v94, v95
	v_cvt_pk_bf16_f32 v93, v96, v97
	global_store_dwordx4 v[98:99], v[90:93], off nt
	v_cvt_pk_bf16_f32 v82, v82, v83
	v_cvt_pk_bf16_f32 v83, v84, v85
	v_cvt_pk_bf16_f32 v84, v74, v75
	v_or_b32_e32 v74, 48, v155
	v_mad_i64_i32 v[74:75], s[22:23], s13, v74, 0
	v_cvt_pk_bf16_f32 v85, v76, v77
	global_store_dwordx4 v[98:99], v[82:85], off offset:256 nt
	s_nop 1
	v_lshl_add_u64 v[82:83], v[74:75], 1, v[146:147]
	v_cvt_pk_bf16_f32 v74, v86, v87
	v_cvt_pk_bf16_f32 v75, v88, v89
	v_cvt_pk_bf16_f32 v76, v78, v79
	v_cvt_pk_bf16_f32 v77, v80, v81
	global_store_dwordx4 v[82:83], v[74:77], off nt
	v_cvt_pk_bf16_f32 v70, v70, v71
	v_cvt_pk_bf16_f32 v71, v72, v73
	v_cvt_pk_bf16_f32 v72, v66, v67
	v_add_u32_e32 v66, 0x80, v155
	v_mad_i64_i32 v[66:67], s[22:23], s13, v66, 0
	v_lshl_add_u64 v[66:67], v[66:67], 1, v[146:147]
	v_cvt_pk_bf16_f32 v73, v68, v69
	global_store_dwordx4 v[82:83], v[70:73], off offset:256 nt
	v_cvt_pk_bf16_f32 v62, v62, v63
	v_cvt_pk_bf16_f32 v63, v64, v65
	v_cvt_pk_bf16_f32 v64, v58, v59
	v_cvt_pk_bf16_f32 v65, v60, v61
	global_store_dwordx4 v[66:67], v[62:65], off nt
	v_cvt_pk_bf16_f32 v50, v50, v51
	v_cvt_pk_bf16_f32 v51, v52, v53
	v_cvt_pk_bf16_f32 v52, v42, v43
	v_add_u32_e32 v42, 0x90, v155
	v_mad_i64_i32 v[42:43], s[22:23], s13, v42, 0
	v_cvt_pk_bf16_f32 v53, v44, v45
	global_store_dwordx4 v[66:67], v[50:53], off offset:256 nt
	s_nop 1
	v_lshl_add_u64 v[50:51], v[42:43], 1, v[146:147]
	v_cvt_pk_bf16_f32 v42, v54, v55
	v_cvt_pk_bf16_f32 v43, v56, v57
	v_cvt_pk_bf16_f32 v44, v46, v47
	v_cvt_pk_bf16_f32 v45, v48, v49
	global_store_dwordx4 v[50:51], v[42:45], off nt
	v_cvt_pk_bf16_f32 v34, v34, v35
	v_cvt_pk_bf16_f32 v35, v36, v37
	v_cvt_pk_bf16_f32 v36, v26, v27
	v_add_u32_e32 v26, 0xa0, v155
	v_mad_i64_i32 v[26:27], s[22:23], s13, v26, 0
	v_cvt_pk_bf16_f32 v37, v28, v29
	global_store_dwordx4 v[50:51], v[34:37], off offset:256 nt
	s_nop 1
	v_lshl_add_u64 v[34:35], v[26:27], 1, v[146:147]
	v_cvt_pk_bf16_f32 v26, v38, v39
	v_cvt_pk_bf16_f32 v27, v40, v41
	v_cvt_pk_bf16_f32 v28, v30, v31
	v_cvt_pk_bf16_f32 v29, v32, v33
	global_store_dwordx4 v[34:35], v[26:29], off nt
	v_cvt_pk_bf16_f32 v18, v18, v19
	v_cvt_pk_bf16_f32 v19, v20, v21
	v_cvt_pk_bf16_f32 v20, v10, v11
	v_add_u32_e32 v10, 0xb0, v155
	v_mad_i64_i32 v[10:11], s[22:23], s13, v10, 0
	v_cvt_pk_bf16_f32 v21, v12, v13
	global_store_dwordx4 v[34:35], v[18:21], off offset:256 nt
	s_nop 1
	v_lshl_add_u64 v[18:19], v[10:11], 1, v[146:147]
	v_cvt_pk_bf16_f32 v10, v22, v23
	v_cvt_pk_bf16_f32 v11, v24, v25
	v_cvt_pk_bf16_f32 v12, v14, v15
	v_cvt_pk_bf16_f32 v13, v16, v17
	global_store_dwordx4 v[18:19], v[10:13], off nt
	v_cvt_pk_bf16_f32 v6, v6, v7
	v_cvt_pk_bf16_f32 v7, v8, v9
	v_cvt_pk_bf16_f32 v8, v2, v3
	v_cvt_pk_bf16_f32 v9, v4, v5
	global_store_dwordx4 v[18:19], v[6:9], off offset:256 nt
	s_cbranch_vccnz .LBB0_119
	s_andn2_b64 vcc, exec, s[6:7]
	s_cbranch_vccnz .LBB0_118
	s_barrier
	s_branch .LBB0_118

.LBB0_378:
	s_add_u32 s24, s78, s24
	v_lshl_add_u32 v154, s42, 8, v1
	v_add_u32_e32 v156, s27, v147
	s_addc_u32 s25, s79, s25
	v_ashrrev_i32_e32 v157, 31, v156
	v_ashrrev_i32_e32 v155, 31, v154
	v_lshl_add_u64 v[156:157], v[156:157], 1, s[24:25]
	v_lshlrev_b64 v[158:159], 11, v[154:155]
	v_lshl_add_u64 v[158:159], v[156:157], 0, v[158:159]
	s_mov_b32 s12, 0x40000
	v_cvt_pk_f16_f32 v62, v62, v63
	v_cvt_pk_f16_f32 v63, v64, v65
	v_cvt_pk_f16_f32 v64, v58, v59
	v_add_co_u32_e32 v58, vcc, s12, v158
	s_mov_b32 s12, 0x48000
	s_nop 0
	v_addc_co_u32_e32 v59, vcc, 0, v159, vcc
	v_cvt_pk_f16_f32 v46, v46, v47
	v_cvt_pk_f16_f32 v47, v48, v49
	v_cvt_pk_f16_f32 v48, v42, v43
	v_add_co_u32_e32 v42, vcc, s12, v158
	s_mov_b32 s12, 0x50000
	s_nop 0
	v_addc_co_u32_e32 v43, vcc, 0, v159, vcc
	s_mov_b64 s[24:25], 0x40000
	v_cvt_pk_f16_f32 v30, v30, v31
	v_cvt_pk_f16_f32 v31, v32, v33
	v_cvt_pk_f16_f32 v32, v26, v27
	v_add_co_u32_e32 v26, vcc, s12, v158
	v_cvt_pk_f16_f32 v118, v118, v119
	v_cvt_pk_f16_f32 v119, v120, v121
	v_cvt_pk_f16_f32 v120, v114, v115
	v_or_b32_e32 v114, 16, v154
	v_cvt_pk_f16_f32 v102, v102, v103
	v_cvt_pk_f16_f32 v103, v104, v105
	v_cvt_pk_f16_f32 v104, v98, v99
	v_or_b32_e32 v98, 32, v154
	v_cvt_pk_f16_f32 v86, v86, v87
	v_cvt_pk_f16_f32 v87, v88, v89
	v_cvt_pk_f16_f32 v88, v82, v83
	v_or_b32_e32 v82, 48, v154
	v_cvt_pk_f16_f32 v70, v70, v71
	v_cvt_pk_f16_f32 v71, v72, v73
	v_cvt_pk_f16_f32 v72, v66, v67
	v_lshl_add_u64 v[66:67], v[158:159], 0, s[24:25]
	s_mov_b64 s[24:25], 0x48000
	v_addc_co_u32_e32 v27, vcc, 0, v159, vcc
	v_ashrrev_i32_e32 v115, 31, v114
	v_ashrrev_i32_e32 v99, 31, v98
	v_ashrrev_i32_e32 v83, 31, v82
	v_cvt_pk_f16_f32 v54, v54, v55
	v_cvt_pk_f16_f32 v55, v56, v57
	v_cvt_pk_f16_f32 v56, v50, v51
	v_lshl_add_u64 v[50:51], v[158:159], 0, s[24:25]
	s_mov_b64 s[24:25], 0x50000
	v_cvt_pk_f16_f32 v14, v14, v15
	v_cvt_pk_f16_f32 v15, v16, v17
	v_cvt_pk_f16_f32 v16, v10, v11
	v_add_co_u32_e32 v10, vcc, 0x58000, v158
	v_lshlrev_b64 v[114:115], 11, v[114:115]
	v_lshlrev_b64 v[98:99], 11, v[98:99]
	v_lshlrev_b64 v[82:83], 11, v[82:83]
	v_cvt_pk_f16_f32 v38, v38, v39
	v_cvt_pk_f16_f32 v39, v40, v41
	v_cvt_pk_f16_f32 v40, v34, v35
	v_lshl_add_u64 v[34:35], v[158:159], 0, s[24:25]
	s_mov_b64 s[24:25], 0x58000
	v_addc_co_u32_e32 v11, vcc, 0, v159, vcc
	v_cvt_pk_f16_f32 v122, v122, v123
	v_cvt_pk_f16_f32 v123, v124, v125
	v_cvt_pk_f16_f32 v124, v126, v127
	v_cvt_pk_f16_f32 v125, v128, v129
	v_cvt_pk_f16_f32 v121, v116, v117
	v_lshl_add_u64 v[114:115], v[156:157], 0, v[114:115]
	v_cvt_pk_f16_f32 v110, v110, v111
	v_cvt_pk_f16_f32 v111, v112, v113
	v_cvt_pk_f16_f32 v112, v106, v107
	v_cvt_pk_f16_f32 v113, v108, v109
	v_cvt_pk_f16_f32 v105, v100, v101
	v_lshl_add_u64 v[98:99], v[156:157], 0, v[98:99]
	v_cvt_pk_f16_f32 v94, v94, v95
	v_cvt_pk_f16_f32 v95, v96, v97
	v_cvt_pk_f16_f32 v96, v90, v91
	v_cvt_pk_f16_f32 v97, v92, v93
	v_cvt_pk_f16_f32 v89, v84, v85
	v_lshl_add_u64 v[82:83], v[156:157], 0, v[82:83]
	v_cvt_pk_f16_f32 v78, v78, v79
	v_cvt_pk_f16_f32 v79, v80, v81
	v_cvt_pk_f16_f32 v80, v74, v75
	v_cvt_pk_f16_f32 v81, v76, v77
	v_cvt_pk_f16_f32 v73, v68, v69
	v_cvt_pk_f16_f32 v65, v60, v61
	v_cvt_pk_f16_f32 v57, v52, v53
	v_cvt_pk_f16_f32 v49, v44, v45
	v_cvt_pk_f16_f32 v41, v36, v37
	v_cvt_pk_f16_f32 v33, v28, v29
	v_cvt_pk_f16_f32 v22, v22, v23
	v_cvt_pk_f16_f32 v23, v24, v25
	v_cvt_pk_f16_f32 v24, v18, v19
	v_cvt_pk_f16_f32 v25, v20, v21
	v_lshl_add_u64 v[18:19], v[158:159], 0, s[24:25]
	v_cvt_pk_f16_f32 v17, v12, v13
	v_cvt_pk_f16_f32 v6, v6, v7
	v_cvt_pk_f16_f32 v7, v8, v9
	v_cvt_pk_f16_f32 v8, v2, v3
	v_cvt_pk_f16_f32 v9, v4, v5
	s_and_b64 vcc, exec, s[0:1]
	s_mov_b64 s[0:1], -1
	global_store_dwordx4 v[158:159], v[122:125], off nt
	global_store_dwordx4 v[158:159], v[118:121], off offset:256 nt
	global_store_dwordx4 v[114:115], v[110:113], off nt
	global_store_dwordx4 v[114:115], v[102:105], off offset:256 nt
	global_store_dwordx4 v[98:99], v[94:97], off nt
	global_store_dwordx4 v[98:99], v[86:89], off offset:256 nt
	global_store_dwordx4 v[82:83], v[78:81], off nt
	global_store_dwordx4 v[82:83], v[70:73], off offset:256 nt
	global_store_dwordx4 v[58:59], v[62:65], off nt
	global_store_dwordx4 v[66:67], v[54:57], off offset:256 nt
	global_store_dwordx4 v[42:43], v[46:49], off nt
	global_store_dwordx4 v[50:51], v[38:41], off offset:256 nt
	global_store_dwordx4 v[26:27], v[30:33], off nt
	global_store_dwordx4 v[34:35], v[22:25], off offset:256 nt
	global_store_dwordx4 v[10:11], v[14:17], off nt
	global_store_dwordx4 v[18:19], v[6:9], off offset:256 nt
	s_cbranch_vccnz .LBB0_362
	s_andn2_b64 vcc, exec, s[14:15]
	s_cbranch_vccnz .LBB0_361
	s_barrier
	s_branch .LBB0_361

.LBB0_890:
	v_lshl_add_u32 v156, s30, 8, v1
	v_lshl_or_b32 v146, s58, 8, v150
	v_ashrrev_i32_e32 v147, 31, v146
	v_ashrrev_i32_e32 v157, 31, v156
	v_lshl_add_u64 v[158:159], v[146:147], 1, s[10:11]
	v_lshlrev_b64 v[146:147], 12, v[156:157]
	v_lshl_add_u64 v[146:147], v[158:159], 0, v[146:147]
	v_cvt_pk_bf16_f32 v126, v126, v127
	v_cvt_pk_bf16_f32 v127, v128, v129
	v_cvt_pk_bf16_f32 v128, v122, v123
	v_cvt_pk_bf16_f32 v129, v124, v125
	global_store_dwordx4 v[146:147], v[126:129], off nt
	v_cvt_pk_bf16_f32 v114, v114, v115
	v_cvt_pk_bf16_f32 v115, v116, v117
	v_cvt_pk_bf16_f32 v116, v106, v107
	v_or_b32_e32 v106, 16, v156
	v_ashrrev_i32_e32 v107, 31, v106
	v_lshlrev_b64 v[106:107], 12, v[106:107]
	v_cvt_pk_bf16_f32 v117, v108, v109
	global_store_dwordx4 v[146:147], v[114:117], off offset:256 nt
	s_nop 1
	v_lshl_add_u64 v[114:115], v[158:159], 0, v[106:107]
	v_cvt_pk_bf16_f32 v106, v118, v119
	v_cvt_pk_bf16_f32 v107, v120, v121
	v_cvt_pk_bf16_f32 v108, v110, v111
	v_cvt_pk_bf16_f32 v109, v112, v113
	global_store_dwordx4 v[114:115], v[106:109], off nt
	v_cvt_pk_bf16_f32 v98, v98, v99
	v_cvt_pk_bf16_f32 v99, v100, v101
	v_cvt_pk_bf16_f32 v100, v90, v91
	v_or_b32_e32 v90, 32, v156
	v_ashrrev_i32_e32 v91, 31, v90
	v_lshlrev_b64 v[90:91], 12, v[90:91]
	v_cvt_pk_bf16_f32 v101, v92, v93
	global_store_dwordx4 v[114:115], v[98:101], off offset:256 nt
	s_nop 1
	v_lshl_add_u64 v[98:99], v[158:159], 0, v[90:91]
	v_cvt_pk_bf16_f32 v90, v102, v103
	v_cvt_pk_bf16_f32 v91, v104, v105
	v_cvt_pk_bf16_f32 v92, v94, v95
	v_cvt_pk_bf16_f32 v93, v96, v97
	global_store_dwordx4 v[98:99], v[90:93], off nt
	v_cvt_pk_bf16_f32 v82, v82, v83
	v_cvt_pk_bf16_f32 v83, v84, v85
	v_cvt_pk_bf16_f32 v84, v74, v75
	v_or_b32_e32 v74, 48, v156
	v_ashrrev_i32_e32 v75, 31, v74
	v_lshlrev_b64 v[74:75], 12, v[74:75]
	v_cvt_pk_bf16_f32 v85, v76, v77
	global_store_dwordx4 v[98:99], v[82:85], off offset:256 nt
	s_nop 1
	v_lshl_add_u64 v[82:83], v[158:159], 0, v[74:75]
	v_cvt_pk_bf16_f32 v74, v86, v87
	v_cvt_pk_bf16_f32 v75, v88, v89
	v_cvt_pk_bf16_f32 v76, v78, v79
	v_cvt_pk_bf16_f32 v77, v80, v81
	global_store_dwordx4 v[82:83], v[74:77], off nt
	v_cvt_pk_bf16_f32 v70, v70, v71
	v_cvt_pk_bf16_f32 v71, v72, v73
	v_cvt_pk_bf16_f32 v72, v66, v67
	v_cvt_pk_bf16_f32 v73, v68, v69
	global_store_dwordx4 v[82:83], v[70:73], off offset:256 nt
	v_cvt_pk_bf16_f32 v62, v62, v63
	v_cvt_pk_bf16_f32 v63, v64, v65
	v_cvt_pk_bf16_f32 v64, v58, v59
	v_add_co_u32_e32 v58, vcc, s54, v146
	v_lshl_add_u64 v[66:67], v[146:147], 0, s[6:7]
	s_nop 0
	v_addc_co_u32_e32 v59, vcc, 0, v147, vcc
	v_cvt_pk_bf16_f32 v65, v60, v61
	global_store_dwordx4 v[58:59], v[62:65], off nt
	v_cvt_pk_bf16_f32 v50, v50, v51
	v_cvt_pk_bf16_f32 v51, v52, v53
	v_cvt_pk_bf16_f32 v52, v42, v43
	v_cvt_pk_bf16_f32 v53, v44, v45
	global_store_dwordx4 v[66:67], v[50:53], off offset:256 nt
	v_cvt_pk_bf16_f32 v42, v54, v55
	v_cvt_pk_bf16_f32 v43, v56, v57
	v_cvt_pk_bf16_f32 v44, v46, v47
	v_add_co_u32_e32 v46, vcc, s55, v146
	s_nop 0
	v_lshl_add_u64 v[50:51], v[146:147], 0, s[16:17]
	v_addc_co_u32_e32 v47, vcc, 0, v147, vcc
	v_cvt_pk_bf16_f32 v45, v48, v49
	global_store_dwordx4 v[46:47], v[42:45], off nt
	v_cvt_pk_bf16_f32 v34, v34, v35
	v_cvt_pk_bf16_f32 v35, v36, v37
	v_cvt_pk_bf16_f32 v36, v26, v27
	v_cvt_pk_bf16_f32 v37, v28, v29
	global_store_dwordx4 v[50:51], v[34:37], off offset:256 nt
	v_cvt_pk_bf16_f32 v26, v38, v39
	v_cvt_pk_bf16_f32 v27, v40, v41
	v_cvt_pk_bf16_f32 v28, v30, v31
	v_add_co_u32_e32 v30, vcc, s56, v146
	s_nop 0
	v_lshl_add_u64 v[34:35], v[146:147], 0, s[18:19]
	v_addc_co_u32_e32 v31, vcc, 0, v147, vcc
	v_cvt_pk_bf16_f32 v29, v32, v33
	global_store_dwordx4 v[30:31], v[26:29], off nt
	v_cvt_pk_bf16_f32 v18, v18, v19
	v_cvt_pk_bf16_f32 v19, v20, v21
	v_cvt_pk_bf16_f32 v20, v10, v11
	v_cvt_pk_bf16_f32 v21, v12, v13
	global_store_dwordx4 v[34:35], v[18:21], off offset:256 nt
	v_cvt_pk_bf16_f32 v10, v22, v23
	v_cvt_pk_bf16_f32 v11, v24, v25
	v_cvt_pk_bf16_f32 v12, v14, v15
	v_add_co_u32_e32 v14, vcc, s57, v146
	s_nop 0
	v_lshl_add_u64 v[18:19], v[146:147], 0, s[20:21]
	v_addc_co_u32_e32 v15, vcc, 0, v147, vcc
	s_andn2_b64 vcc, exec, s[0:1]
	s_mov_b64 s[0:1], -1
	v_cvt_pk_bf16_f32 v13, v16, v17
	global_store_dwordx4 v[14:15], v[10:13], off nt
	v_cvt_pk_bf16_f32 v6, v6, v7
	v_cvt_pk_bf16_f32 v7, v8, v9
	v_cvt_pk_bf16_f32 v8, v2, v3
	v_cvt_pk_bf16_f32 v9, v4, v5
	global_store_dwordx4 v[18:19], v[6:9], off offset:256 nt
	s_cbranch_vccnz .LBB0_879
	s_andn2_b64 vcc, exec, s[8:9]
	s_cbranch_vccnz .LBB0_878
	s_barrier
	s_branch .LBB0_878

.LBB0_1085:
	v_lshl_add_u32 v156, s30, 8, v1
	v_lshl_or_b32 v146, s58, 8, v150
	v_max_f32_e32 v122, v122, v122
	v_ashrrev_i32_e32 v147, 31, v146
	v_ashrrev_i32_e32 v157, 31, v156
	v_max_f32_e32 v122, 0, v122
	v_max_f32_e32 v123, v123, v123
	v_max_f32_e32 v124, v124, v124
	v_lshl_add_u64 v[158:159], v[146:147], 1, s[8:9]
	v_lshlrev_b64 v[146:147], 14, v[156:157]
	v_mul_f32_e32 v157, v122, v122
	v_max_f32_e32 v122, v127, v127
	v_max_f32_e32 v123, 0, v123
	v_max_f32_e32 v124, 0, v124
	v_max_f32_e32 v126, v126, v126
	v_max_f32_e32 v122, 0, v122
	v_mul_f32_e32 v127, v123, v123
	v_max_f32_e32 v123, v128, v128
	v_mul_f32_e32 v128, v124, v124
	v_max_f32_e32 v124, v129, v129
	v_max_f32_e32 v125, v125, v125
	v_max_f32_e32 v126, 0, v126
	v_mul_f32_e32 v122, v122, v122
	v_max_f32_e32 v123, 0, v123
	v_max_f32_e32 v124, 0, v124
	v_max_f32_e32 v125, 0, v125
	v_max_f32_e32 v114, v114, v114
	v_max_f32_e32 v115, v115, v115
	v_max_f32_e32 v116, v116, v116
	v_lshl_add_u64 v[146:147], v[158:159], 0, v[146:147]
	v_mul_f32_e32 v126, v126, v126
	v_mul_f32_e32 v123, v123, v123
	v_mul_f32_e32 v124, v124, v124
	v_mul_f32_e32 v125, v125, v125
	v_cvt_pk_bf16_f32 v122, v126, v122
	v_max_f32_e32 v114, 0, v114
	v_max_f32_e32 v115, 0, v115
	v_max_f32_e32 v116, 0, v116
	v_cvt_pk_bf16_f32 v123, v123, v124
	v_cvt_pk_bf16_f32 v124, v157, v127
	v_cvt_pk_bf16_f32 v125, v128, v125
	global_store_dwordx4 v[146:147], v[122:125], off nt
	v_max_f32_e32 v118, v118, v118
	v_max_f32_e32 v117, v117, v117
	v_mul_f32_e32 v122, v114, v114
	v_max_f32_e32 v114, v119, v119
	v_mul_f32_e32 v119, v115, v115
	v_max_f32_e32 v115, v120, v120
	v_mul_f32_e32 v120, v116, v116
	v_max_f32_e32 v116, v121, v121
	v_max_f32_e32 v114, 0, v114
	v_max_f32_e32 v115, 0, v115
	v_max_f32_e32 v116, 0, v116
	v_max_f32_e32 v118, 0, v118
	v_mul_f32_e32 v114, v114, v114
	v_mul_f32_e32 v115, v115, v115
	v_max_f32_e32 v117, 0, v117
	v_mul_f32_e32 v116, v116, v116
	v_max_f32_e32 v106, v106, v106
	v_mul_f32_e32 v118, v118, v118
	v_mul_f32_e32 v117, v117, v117
	v_cvt_pk_bf16_f32 v114, v118, v114
	v_cvt_pk_bf16_f32 v115, v115, v116
	v_cvt_pk_bf16_f32 v116, v122, v119
	v_max_f32_e32 v106, 0, v106
	v_max_f32_e32 v107, v107, v107
	v_max_f32_e32 v108, v108, v108
	v_cvt_pk_bf16_f32 v117, v120, v117
	global_store_dwordx4 v[146:147], v[114:117], off offset:256 nt
	v_max_f32_e32 v107, 0, v107
	v_max_f32_e32 v108, 0, v108
	v_or_b32_e32 v114, 16, v156
	v_mul_f32_e32 v116, v106, v106
	v_max_f32_e32 v106, v111, v111
	v_ashrrev_i32_e32 v115, 31, v114
	v_max_f32_e32 v110, v110, v110
	v_max_f32_e32 v106, 0, v106
	v_mul_f32_e32 v111, v107, v107
	v_max_f32_e32 v107, v112, v112
	v_mul_f32_e32 v112, v108, v108
	v_max_f32_e32 v108, v113, v113
	v_max_f32_e32 v109, v109, v109
	v_lshlrev_b64 v[114:115], 14, v[114:115]
	v_max_f32_e32 v110, 0, v110
	v_mul_f32_e32 v106, v106, v106
	v_max_f32_e32 v107, 0, v107
	v_max_f32_e32 v108, 0, v108
	v_max_f32_e32 v109, 0, v109
	v_max_f32_e32 v98, v98, v98
	v_max_f32_e32 v99, v99, v99
	v_max_f32_e32 v100, v100, v100
	v_lshl_add_u64 v[114:115], v[158:159], 0, v[114:115]
	v_mul_f32_e32 v110, v110, v110
	v_mul_f32_e32 v107, v107, v107
	v_mul_f32_e32 v108, v108, v108
	v_mul_f32_e32 v109, v109, v109
	v_cvt_pk_bf16_f32 v106, v110, v106
	v_max_f32_e32 v98, 0, v98
	v_max_f32_e32 v99, 0, v99
	v_max_f32_e32 v100, 0, v100
	v_cvt_pk_bf16_f32 v107, v107, v108
	v_cvt_pk_bf16_f32 v108, v116, v111
	v_cvt_pk_bf16_f32 v109, v112, v109
	global_store_dwordx4 v[114:115], v[106:109], off nt
	v_max_f32_e32 v102, v102, v102
	v_max_f32_e32 v101, v101, v101
	v_mul_f32_e32 v106, v98, v98
	v_max_f32_e32 v98, v103, v103
	v_mul_f32_e32 v103, v99, v99
	v_max_f32_e32 v99, v104, v104
	v_mul_f32_e32 v104, v100, v100
	v_max_f32_e32 v100, v105, v105
	v_max_f32_e32 v98, 0, v98
	v_max_f32_e32 v99, 0, v99
	v_max_f32_e32 v100, 0, v100
	v_max_f32_e32 v102, 0, v102
	v_mul_f32_e32 v98, v98, v98
	v_mul_f32_e32 v99, v99, v99
	v_max_f32_e32 v101, 0, v101
	v_mul_f32_e32 v100, v100, v100
	v_max_f32_e32 v90, v90, v90
	v_mul_f32_e32 v102, v102, v102
	v_mul_f32_e32 v101, v101, v101
	v_cvt_pk_bf16_f32 v98, v102, v98
	v_cvt_pk_bf16_f32 v99, v99, v100
	v_cvt_pk_bf16_f32 v100, v106, v103
	v_max_f32_e32 v90, 0, v90
	v_max_f32_e32 v91, v91, v91
	v_max_f32_e32 v92, v92, v92
	v_cvt_pk_bf16_f32 v101, v104, v101
	global_store_dwordx4 v[114:115], v[98:101], off offset:256 nt
	v_max_f32_e32 v91, 0, v91
	v_max_f32_e32 v92, 0, v92
	v_or_b32_e32 v98, 32, v156
	v_mul_f32_e32 v100, v90, v90
	v_max_f32_e32 v90, v95, v95
	v_ashrrev_i32_e32 v99, 31, v98
	v_max_f32_e32 v94, v94, v94
	v_max_f32_e32 v90, 0, v90
	v_mul_f32_e32 v95, v91, v91
	v_max_f32_e32 v91, v96, v96
	v_mul_f32_e32 v96, v92, v92
	v_max_f32_e32 v92, v97, v97
	v_max_f32_e32 v93, v93, v93
	v_lshlrev_b64 v[98:99], 14, v[98:99]
	v_max_f32_e32 v94, 0, v94
	v_mul_f32_e32 v90, v90, v90
	v_max_f32_e32 v91, 0, v91
	v_max_f32_e32 v92, 0, v92
	v_max_f32_e32 v93, 0, v93
	v_max_f32_e32 v82, v82, v82
	v_max_f32_e32 v83, v83, v83
	v_max_f32_e32 v84, v84, v84
	v_lshl_add_u64 v[98:99], v[158:159], 0, v[98:99]
	v_mul_f32_e32 v94, v94, v94
	v_mul_f32_e32 v91, v91, v91
	v_mul_f32_e32 v92, v92, v92
	v_mul_f32_e32 v93, v93, v93
	v_cvt_pk_bf16_f32 v90, v94, v90
	v_max_f32_e32 v82, 0, v82
	v_max_f32_e32 v83, 0, v83
	v_max_f32_e32 v84, 0, v84
	v_cvt_pk_bf16_f32 v91, v91, v92
	v_cvt_pk_bf16_f32 v92, v100, v95
	v_cvt_pk_bf16_f32 v93, v96, v93
	global_store_dwordx4 v[98:99], v[90:93], off nt
	v_max_f32_e32 v86, v86, v86
	v_max_f32_e32 v85, v85, v85
	v_mul_f32_e32 v90, v82, v82
	v_max_f32_e32 v82, v87, v87
	v_mul_f32_e32 v87, v83, v83
	v_max_f32_e32 v83, v88, v88
	v_mul_f32_e32 v88, v84, v84
	v_max_f32_e32 v84, v89, v89
	v_max_f32_e32 v82, 0, v82
	v_max_f32_e32 v83, 0, v83
	v_max_f32_e32 v84, 0, v84
	v_max_f32_e32 v86, 0, v86
	v_mul_f32_e32 v82, v82, v82
	v_mul_f32_e32 v83, v83, v83
	v_max_f32_e32 v85, 0, v85
	v_mul_f32_e32 v84, v84, v84
	v_max_f32_e32 v74, v74, v74
	v_mul_f32_e32 v86, v86, v86
	v_mul_f32_e32 v85, v85, v85
	v_cvt_pk_bf16_f32 v82, v86, v82
	v_cvt_pk_bf16_f32 v83, v83, v84
	v_cvt_pk_bf16_f32 v84, v90, v87
	v_max_f32_e32 v74, 0, v74
	v_max_f32_e32 v75, v75, v75
	v_max_f32_e32 v76, v76, v76
	v_cvt_pk_bf16_f32 v85, v88, v85
	global_store_dwordx4 v[98:99], v[82:85], off offset:256 nt
	v_max_f32_e32 v75, 0, v75
	v_max_f32_e32 v76, 0, v76
	v_or_b32_e32 v82, 48, v156
	v_mul_f32_e32 v84, v74, v74
	v_max_f32_e32 v74, v79, v79
	v_ashrrev_i32_e32 v83, 31, v82
	v_max_f32_e32 v78, v78, v78
	v_max_f32_e32 v74, 0, v74
	v_mul_f32_e32 v79, v75, v75
	v_max_f32_e32 v75, v80, v80
	v_mul_f32_e32 v80, v76, v76
	v_max_f32_e32 v76, v81, v81
	v_max_f32_e32 v77, v77, v77
	v_lshlrev_b64 v[82:83], 14, v[82:83]
	v_max_f32_e32 v78, 0, v78
	v_mul_f32_e32 v74, v74, v74
	v_max_f32_e32 v75, 0, v75
	v_max_f32_e32 v76, 0, v76
	v_max_f32_e32 v77, 0, v77
	v_max_f32_e32 v66, v66, v66
	v_max_f32_e32 v67, v67, v67
	v_max_f32_e32 v68, v68, v68
	v_lshl_add_u64 v[82:83], v[158:159], 0, v[82:83]
	v_mul_f32_e32 v78, v78, v78
	v_mul_f32_e32 v75, v75, v75
	v_mul_f32_e32 v76, v76, v76
	v_mul_f32_e32 v77, v77, v77
	v_cvt_pk_bf16_f32 v74, v78, v74
	v_max_f32_e32 v66, 0, v66
	v_max_f32_e32 v67, 0, v67
	v_max_f32_e32 v68, 0, v68
	v_cvt_pk_bf16_f32 v75, v75, v76
	v_cvt_pk_bf16_f32 v76, v84, v79
	v_cvt_pk_bf16_f32 v77, v80, v77
	global_store_dwordx4 v[82:83], v[74:77], off nt
	v_max_f32_e32 v70, v70, v70
	v_max_f32_e32 v69, v69, v69
	v_mul_f32_e32 v74, v66, v66
	v_max_f32_e32 v66, v71, v71
	v_mul_f32_e32 v71, v67, v67
	v_max_f32_e32 v67, v72, v72
	v_mul_f32_e32 v72, v68, v68
	v_max_f32_e32 v68, v73, v73
	v_max_f32_e32 v66, 0, v66
	v_max_f32_e32 v67, 0, v67
	v_max_f32_e32 v68, 0, v68
	v_max_f32_e32 v70, 0, v70
	v_mul_f32_e32 v66, v66, v66
	v_mul_f32_e32 v67, v67, v67
	v_max_f32_e32 v69, 0, v69
	v_mul_f32_e32 v68, v68, v68
	v_max_f32_e32 v58, v58, v58
	v_mul_f32_e32 v70, v70, v70
	v_mul_f32_e32 v69, v69, v69
	v_cvt_pk_bf16_f32 v66, v70, v66
	v_cvt_pk_bf16_f32 v67, v67, v68
	v_cvt_pk_bf16_f32 v68, v74, v71
	v_max_f32_e32 v58, 0, v58
	v_max_f32_e32 v59, v59, v59
	v_max_f32_e32 v60, v60, v60
	v_cvt_pk_bf16_f32 v69, v72, v69
	global_store_dwordx4 v[82:83], v[66:69], off offset:256 nt
	v_max_f32_e32 v62, v62, v62
	v_max_f32_e32 v59, 0, v59
	v_mul_f32_e32 v68, v58, v58
	v_max_f32_e32 v58, v63, v63
	v_max_f32_e32 v60, 0, v60
	v_max_f32_e32 v62, 0, v62
	v_max_f32_e32 v58, 0, v58
	v_mul_f32_e32 v63, v59, v59
	v_max_f32_e32 v59, v64, v64
	v_mul_f32_e32 v64, v60, v60
	v_max_f32_e32 v60, v65, v65
	v_mul_f32_e32 v62, v62, v62
	v_mul_f32_e32 v58, v58, v58
	v_max_f32_e32 v59, 0, v59
	v_max_f32_e32 v60, 0, v60
	v_max_f32_e32 v61, v61, v61
	v_mul_f32_e32 v59, v59, v59
	v_max_f32_e32 v61, 0, v61
	v_mul_f32_e32 v60, v60, v60
	v_cvt_pk_bf16_f32 v58, v62, v58
	v_add_co_u32_e32 v62, vcc, s54, v146
	v_max_f32_e32 v50, v50, v50
	v_max_f32_e32 v51, v51, v51
	v_max_f32_e32 v52, v52, v52
	v_mul_f32_e32 v61, v61, v61
	v_cvt_pk_bf16_f32 v59, v59, v60
	v_cvt_pk_bf16_f32 v60, v68, v63
	v_addc_co_u32_e32 v63, vcc, 0, v147, vcc
	v_max_f32_e32 v50, 0, v50
	v_max_f32_e32 v51, 0, v51
	v_max_f32_e32 v52, 0, v52
	v_cvt_pk_bf16_f32 v61, v64, v61
	global_store_dwordx4 v[62:63], v[58:61], off nt
	v_max_f32_e32 v54, v54, v54
	v_max_f32_e32 v53, v53, v53
	v_mul_f32_e32 v58, v50, v50
	v_max_f32_e32 v50, v55, v55
	v_mul_f32_e32 v55, v51, v51
	v_max_f32_e32 v51, v56, v56
	v_mul_f32_e32 v56, v52, v52
	v_max_f32_e32 v52, v57, v57
	v_max_f32_e32 v50, 0, v50
	v_max_f32_e32 v51, 0, v51
	v_max_f32_e32 v52, 0, v52
	v_max_f32_e32 v54, 0, v54
	v_mul_f32_e32 v50, v50, v50
	v_mul_f32_e32 v51, v51, v51
	v_max_f32_e32 v53, 0, v53
	v_mul_f32_e32 v52, v52, v52
	v_max_f32_e32 v42, v42, v42
	v_lshl_add_u64 v[66:67], v[146:147], 0, s[14:15]
	v_mul_f32_e32 v54, v54, v54
	v_mul_f32_e32 v53, v53, v53
	v_cvt_pk_bf16_f32 v50, v54, v50
	v_cvt_pk_bf16_f32 v51, v51, v52
	v_cvt_pk_bf16_f32 v52, v58, v55
	v_max_f32_e32 v42, 0, v42
	v_max_f32_e32 v43, v43, v43
	v_max_f32_e32 v44, v44, v44
	v_cvt_pk_bf16_f32 v53, v56, v53
	global_store_dwordx4 v[66:67], v[50:53], off offset:256 nt
	v_max_f32_e32 v46, v46, v46
	v_max_f32_e32 v43, 0, v43
	v_mul_f32_e32 v52, v42, v42
	v_max_f32_e32 v42, v47, v47
	v_max_f32_e32 v44, 0, v44
	v_max_f32_e32 v46, 0, v46
	v_max_f32_e32 v42, 0, v42
	v_mul_f32_e32 v47, v43, v43
	v_max_f32_e32 v43, v48, v48
	v_mul_f32_e32 v48, v44, v44
	v_max_f32_e32 v44, v49, v49
	v_mul_f32_e32 v46, v46, v46
	v_mul_f32_e32 v42, v42, v42
	v_max_f32_e32 v43, 0, v43
	v_max_f32_e32 v44, 0, v44
	v_max_f32_e32 v45, v45, v45
	v_mul_f32_e32 v43, v43, v43
	v_max_f32_e32 v45, 0, v45
	v_mul_f32_e32 v44, v44, v44
	v_cvt_pk_bf16_f32 v42, v46, v42
	v_add_co_u32_e32 v46, vcc, s55, v146
	v_max_f32_e32 v34, v34, v34
	v_max_f32_e32 v35, v35, v35
	v_max_f32_e32 v36, v36, v36
	v_mul_f32_e32 v45, v45, v45
	v_cvt_pk_bf16_f32 v43, v43, v44
	v_cvt_pk_bf16_f32 v44, v52, v47
	v_addc_co_u32_e32 v47, vcc, 0, v147, vcc
	v_max_f32_e32 v34, 0, v34
	v_max_f32_e32 v35, 0, v35
	v_max_f32_e32 v36, 0, v36
	v_cvt_pk_bf16_f32 v45, v48, v45
	global_store_dwordx4 v[46:47], v[42:45], off nt
	v_max_f32_e32 v38, v38, v38
	v_max_f32_e32 v37, v37, v37
	v_mul_f32_e32 v42, v34, v34
	v_max_f32_e32 v34, v39, v39
	v_mul_f32_e32 v39, v35, v35
	v_max_f32_e32 v35, v40, v40
	v_mul_f32_e32 v40, v36, v36
	v_max_f32_e32 v36, v41, v41
	v_max_f32_e32 v34, 0, v34
	v_max_f32_e32 v35, 0, v35
	v_max_f32_e32 v36, 0, v36
	v_max_f32_e32 v38, 0, v38
	v_mul_f32_e32 v34, v34, v34
	v_mul_f32_e32 v35, v35, v35
	v_max_f32_e32 v37, 0, v37
	v_mul_f32_e32 v36, v36, v36
	v_max_f32_e32 v26, v26, v26
	v_lshl_add_u64 v[50:51], v[146:147], 0, s[16:17]
	v_mul_f32_e32 v38, v38, v38
	v_mul_f32_e32 v37, v37, v37
	v_cvt_pk_bf16_f32 v34, v38, v34
	v_cvt_pk_bf16_f32 v35, v35, v36
	v_cvt_pk_bf16_f32 v36, v42, v39
	v_max_f32_e32 v26, 0, v26
	v_max_f32_e32 v27, v27, v27
	v_max_f32_e32 v28, v28, v28
	v_cvt_pk_bf16_f32 v37, v40, v37
	global_store_dwordx4 v[50:51], v[34:37], off offset:256 nt
	v_max_f32_e32 v30, v30, v30
	v_max_f32_e32 v27, 0, v27
	v_mul_f32_e32 v36, v26, v26
	v_max_f32_e32 v26, v31, v31
	v_max_f32_e32 v28, 0, v28
	v_max_f32_e32 v30, 0, v30
	v_max_f32_e32 v26, 0, v26
	v_mul_f32_e32 v31, v27, v27
	v_max_f32_e32 v27, v32, v32
	v_mul_f32_e32 v32, v28, v28
	v_max_f32_e32 v28, v33, v33
	v_mul_f32_e32 v30, v30, v30
	v_mul_f32_e32 v26, v26, v26
	v_max_f32_e32 v27, 0, v27
	v_max_f32_e32 v28, 0, v28
	v_max_f32_e32 v29, v29, v29
	v_mul_f32_e32 v27, v27, v27
	v_max_f32_e32 v29, 0, v29
	v_mul_f32_e32 v28, v28, v28
	v_cvt_pk_bf16_f32 v26, v30, v26
	v_add_co_u32_e32 v30, vcc, s56, v146
	v_max_f32_e32 v18, v18, v18
	v_max_f32_e32 v19, v19, v19
	v_max_f32_e32 v20, v20, v20
	v_mul_f32_e32 v29, v29, v29
	v_cvt_pk_bf16_f32 v27, v27, v28
	v_cvt_pk_bf16_f32 v28, v36, v31
	v_addc_co_u32_e32 v31, vcc, 0, v147, vcc
	v_max_f32_e32 v18, 0, v18
	v_max_f32_e32 v19, 0, v19
	v_max_f32_e32 v20, 0, v20
	v_cvt_pk_bf16_f32 v29, v32, v29
	global_store_dwordx4 v[30:31], v[26:29], off nt
	v_max_f32_e32 v22, v22, v22
	v_max_f32_e32 v21, v21, v21
	v_mul_f32_e32 v26, v18, v18
	v_max_f32_e32 v18, v23, v23
	v_mul_f32_e32 v23, v19, v19
	v_max_f32_e32 v19, v24, v24
	v_mul_f32_e32 v24, v20, v20
	v_max_f32_e32 v20, v25, v25
	v_max_f32_e32 v18, 0, v18
	v_max_f32_e32 v19, 0, v19
	v_max_f32_e32 v20, 0, v20
	v_max_f32_e32 v22, 0, v22
	v_mul_f32_e32 v18, v18, v18
	v_mul_f32_e32 v19, v19, v19
	v_max_f32_e32 v21, 0, v21
	v_mul_f32_e32 v20, v20, v20
	v_max_f32_e32 v10, v10, v10
	v_lshl_add_u64 v[34:35], v[146:147], 0, s[18:19]
	v_mul_f32_e32 v22, v22, v22
	v_mul_f32_e32 v21, v21, v21
	v_cvt_pk_bf16_f32 v18, v22, v18
	v_cvt_pk_bf16_f32 v19, v19, v20
	v_cvt_pk_bf16_f32 v20, v26, v23
	v_max_f32_e32 v10, 0, v10
	v_max_f32_e32 v11, v11, v11
	v_max_f32_e32 v12, v12, v12
	v_cvt_pk_bf16_f32 v21, v24, v21
	global_store_dwordx4 v[34:35], v[18:21], off offset:256 nt
	v_max_f32_e32 v14, v14, v14
	v_max_f32_e32 v11, 0, v11
	v_mul_f32_e32 v20, v10, v10
	v_max_f32_e32 v10, v15, v15
	v_max_f32_e32 v12, 0, v12
	v_max_f32_e32 v14, 0, v14
	v_max_f32_e32 v10, 0, v10
	v_mul_f32_e32 v15, v11, v11
	v_max_f32_e32 v11, v16, v16
	v_mul_f32_e32 v16, v12, v12
	v_max_f32_e32 v12, v17, v17
	v_mul_f32_e32 v14, v14, v14
	v_mul_f32_e32 v10, v10, v10
	v_max_f32_e32 v11, 0, v11
	v_max_f32_e32 v12, 0, v12
	v_max_f32_e32 v13, v13, v13
	v_mul_f32_e32 v11, v11, v11
	v_max_f32_e32 v13, 0, v13
	v_mul_f32_e32 v12, v12, v12
	v_cvt_pk_bf16_f32 v10, v14, v10
	v_add_co_u32_e32 v14, vcc, s57, v146
	v_max_f32_e32 v2, v2, v2
	v_max_f32_e32 v3, v3, v3
	v_max_f32_e32 v4, v4, v4
	v_mul_f32_e32 v13, v13, v13
	v_cvt_pk_bf16_f32 v11, v11, v12
	v_cvt_pk_bf16_f32 v12, v20, v15
	v_addc_co_u32_e32 v15, vcc, 0, v147, vcc
	v_max_f32_e32 v2, 0, v2
	v_max_f32_e32 v3, 0, v3
	v_max_f32_e32 v4, 0, v4
	v_cvt_pk_bf16_f32 v13, v16, v13
	global_store_dwordx4 v[14:15], v[10:13], off nt
	v_max_f32_e32 v5, v5, v5
	v_max_f32_e32 v6, v6, v6
	v_mul_f32_e32 v10, v2, v2
	v_max_f32_e32 v2, v7, v7
	v_mul_f32_e32 v7, v3, v3
	v_max_f32_e32 v3, v8, v8
	v_mul_f32_e32 v8, v4, v4
	v_max_f32_e32 v4, v9, v9
	v_max_f32_e32 v2, 0, v2
	v_max_f32_e32 v3, 0, v3
	v_max_f32_e32 v4, 0, v4
	v_max_f32_e32 v5, 0, v5
	v_lshl_add_u64 v[18:19], v[146:147], 0, s[20:21]
	v_max_f32_e32 v6, 0, v6
	v_mul_f32_e32 v2, v2, v2
	v_mul_f32_e32 v3, v3, v3
	v_mul_f32_e32 v4, v4, v4
	v_mul_f32_e32 v5, v5, v5
	s_andn2_b64 vcc, exec, s[0:1]
	s_mov_b64 s[0:1], -1
	v_mul_f32_e32 v6, v6, v6
	v_cvt_pk_bf16_f32 v2, v6, v2
	v_cvt_pk_bf16_f32 v3, v3, v4
	v_cvt_pk_bf16_f32 v4, v10, v7
	v_cvt_pk_bf16_f32 v5, v8, v5
	global_store_dwordx4 v[18:19], v[2:5], off offset:256 nt
	s_cbranch_vccnz .LBB0_1074
	s_andn2_b64 vcc, exec, s[6:7]
	s_cbranch_vccnz .LBB0_1073
	s_barrier
	s_branch .LBB0_1073

.LBB0_1193:
	v_lshl_add_u32 v156, s30, 8, v1
	v_lshl_or_b32 v146, s58, 8, v150
	v_ashrrev_i32_e32 v147, 31, v146
	v_ashrrev_i32_e32 v157, 31, v156
	v_lshl_add_u64 v[158:159], v[146:147], 1, s[8:9]
	v_lshlrev_b64 v[146:147], 12, v[156:157]
	v_lshl_add_u64 v[146:147], v[158:159], 0, v[146:147]
	v_cvt_pk_bf16_f32 v126, v126, v127
	v_cvt_pk_bf16_f32 v127, v128, v129
	v_cvt_pk_bf16_f32 v128, v122, v123
	v_cvt_pk_bf16_f32 v129, v124, v125
	global_store_dwordx4 v[146:147], v[126:129], off nt
	v_cvt_pk_bf16_f32 v114, v114, v115
	v_cvt_pk_bf16_f32 v115, v116, v117
	v_cvt_pk_bf16_f32 v116, v106, v107
	v_or_b32_e32 v106, 16, v156
	v_ashrrev_i32_e32 v107, 31, v106
	v_lshlrev_b64 v[106:107], 12, v[106:107]
	v_cvt_pk_bf16_f32 v117, v108, v109
	global_store_dwordx4 v[146:147], v[114:117], off offset:256 nt
	s_nop 1
	v_lshl_add_u64 v[114:115], v[158:159], 0, v[106:107]
	v_cvt_pk_bf16_f32 v106, v118, v119
	v_cvt_pk_bf16_f32 v107, v120, v121
	v_cvt_pk_bf16_f32 v108, v110, v111
	v_cvt_pk_bf16_f32 v109, v112, v113
	global_store_dwordx4 v[114:115], v[106:109], off nt
	v_cvt_pk_bf16_f32 v98, v98, v99
	v_cvt_pk_bf16_f32 v99, v100, v101
	v_cvt_pk_bf16_f32 v100, v90, v91
	v_or_b32_e32 v90, 32, v156
	v_ashrrev_i32_e32 v91, 31, v90
	v_lshlrev_b64 v[90:91], 12, v[90:91]
	v_cvt_pk_bf16_f32 v101, v92, v93
	global_store_dwordx4 v[114:115], v[98:101], off offset:256 nt
	s_nop 1
	v_lshl_add_u64 v[98:99], v[158:159], 0, v[90:91]
	v_cvt_pk_bf16_f32 v90, v102, v103
	v_cvt_pk_bf16_f32 v91, v104, v105
	v_cvt_pk_bf16_f32 v92, v94, v95
	v_cvt_pk_bf16_f32 v93, v96, v97
	global_store_dwordx4 v[98:99], v[90:93], off nt
	v_cvt_pk_bf16_f32 v82, v82, v83
	v_cvt_pk_bf16_f32 v83, v84, v85
	v_cvt_pk_bf16_f32 v84, v74, v75
	v_or_b32_e32 v74, 48, v156
	v_ashrrev_i32_e32 v75, 31, v74
	v_lshlrev_b64 v[74:75], 12, v[74:75]
	v_cvt_pk_bf16_f32 v85, v76, v77
	global_store_dwordx4 v[98:99], v[82:85], off offset:256 nt
	s_nop 1
	v_lshl_add_u64 v[82:83], v[158:159], 0, v[74:75]
	v_cvt_pk_bf16_f32 v74, v86, v87
	v_cvt_pk_bf16_f32 v75, v88, v89
	v_cvt_pk_bf16_f32 v76, v78, v79
	v_cvt_pk_bf16_f32 v77, v80, v81
	global_store_dwordx4 v[82:83], v[74:77], off nt
	v_cvt_pk_bf16_f32 v70, v70, v71
	v_cvt_pk_bf16_f32 v71, v72, v73
	v_cvt_pk_bf16_f32 v72, v66, v67
	v_cvt_pk_bf16_f32 v73, v68, v69
	global_store_dwordx4 v[82:83], v[70:73], off offset:256 nt
	v_cvt_pk_bf16_f32 v62, v62, v63
	v_cvt_pk_bf16_f32 v63, v64, v65
	v_cvt_pk_bf16_f32 v64, v58, v59
	v_add_co_u32_e32 v58, vcc, s54, v146
	v_lshl_add_u64 v[66:67], v[146:147], 0, s[14:15]
	s_nop 0
	v_addc_co_u32_e32 v59, vcc, 0, v147, vcc
	v_cvt_pk_bf16_f32 v65, v60, v61
	global_store_dwordx4 v[58:59], v[62:65], off nt
	v_cvt_pk_bf16_f32 v50, v50, v51
	v_cvt_pk_bf16_f32 v51, v52, v53
	v_cvt_pk_bf16_f32 v52, v42, v43
	v_cvt_pk_bf16_f32 v53, v44, v45
	global_store_dwordx4 v[66:67], v[50:53], off offset:256 nt
	v_cvt_pk_bf16_f32 v42, v54, v55
	v_cvt_pk_bf16_f32 v43, v56, v57
	v_cvt_pk_bf16_f32 v44, v46, v47
	v_add_co_u32_e32 v46, vcc, s55, v146
	s_nop 0
	v_lshl_add_u64 v[50:51], v[146:147], 0, s[16:17]
	v_addc_co_u32_e32 v47, vcc, 0, v147, vcc
	v_cvt_pk_bf16_f32 v45, v48, v49
	global_store_dwordx4 v[46:47], v[42:45], off nt
	v_cvt_pk_bf16_f32 v34, v34, v35
	v_cvt_pk_bf16_f32 v35, v36, v37
	v_cvt_pk_bf16_f32 v36, v26, v27
	v_cvt_pk_bf16_f32 v37, v28, v29
	global_store_dwordx4 v[50:51], v[34:37], off offset:256 nt
	v_cvt_pk_bf16_f32 v26, v38, v39
	v_cvt_pk_bf16_f32 v27, v40, v41
	v_cvt_pk_bf16_f32 v28, v30, v31
	v_add_co_u32_e32 v30, vcc, s56, v146
	s_nop 0
	v_lshl_add_u64 v[34:35], v[146:147], 0, s[18:19]
	v_addc_co_u32_e32 v31, vcc, 0, v147, vcc
	v_cvt_pk_bf16_f32 v29, v32, v33
	global_store_dwordx4 v[30:31], v[26:29], off nt
	v_cvt_pk_bf16_f32 v18, v18, v19
	v_cvt_pk_bf16_f32 v19, v20, v21
	v_cvt_pk_bf16_f32 v20, v10, v11
	v_cvt_pk_bf16_f32 v21, v12, v13
	global_store_dwordx4 v[34:35], v[18:21], off offset:256 nt
	v_cvt_pk_bf16_f32 v10, v22, v23
	v_cvt_pk_bf16_f32 v11, v24, v25
	v_cvt_pk_bf16_f32 v12, v14, v15
	v_add_co_u32_e32 v14, vcc, s57, v146
	s_nop 0
	v_lshl_add_u64 v[18:19], v[146:147], 0, s[20:21]
	v_addc_co_u32_e32 v15, vcc, 0, v147, vcc
	s_andn2_b64 vcc, exec, s[0:1]
	s_mov_b64 s[0:1], -1
	v_cvt_pk_bf16_f32 v13, v16, v17
	global_store_dwordx4 v[14:15], v[10:13], off nt
	v_cvt_pk_bf16_f32 v6, v6, v7
	v_cvt_pk_bf16_f32 v7, v8, v9
	v_cvt_pk_bf16_f32 v8, v2, v3
	v_cvt_pk_bf16_f32 v9, v4, v5
	global_store_dwordx4 v[18:19], v[6:9], off offset:256 nt
	s_cbranch_vccnz .LBB0_1182
	s_andn2_b64 vcc, exec, s[6:7]
	s_cbranch_vccnz .LBB0_1181
	s_barrier
	s_branch .LBB0_1181
